# compressed branch head 1: key-step-0 V^T fragments prefetched ahead of the importance block (two global round trips removed)
# baseline (speedup 1.0000x reference)
; #define MFMA16(a, b, c) __builtin_amdgcn_mfma_f32_16x16x32_f16((a), (b), (c), 0, 0, 0)
; DI float lane_get(float v, int srclane) { return __int_as_float(__builtin_amdgcn_ds_bpermute(srclane << 2, __float_as_int(v))); }
; #define LAS __attribute__((address_space(3)))
; DI float red4_sum(float v, int lane) { v += lane_get(v, lane ^ 16); v += lane_get(v, lane ^ 32); return v; }
; DI void attn_phase(const Params& p, const int layer, const int wid_s) {
;     ...
;         ps = red4_sum(ps, lane);
;         const float inv = ps > 0.f ? 1.f / ps : 0.f;
; #pragma unroll
;         for (int nt = 0; nt < 8; ++nt) s[nt] = s[nt] * inv;
;         if (cur >= 8)
; #pragma unroll
;         for (int nt = 0; nt < 8; ++nt) {
;           const float x1 = lane_get(s[nt][3], (lane - 16) & 63);
;           const float x2 = nt > 0 ? lane_get(s[nt > 0 ? nt - 1 : 0][3], (lane - 16) & 63) : 0.f;
;           const float left = fq > 0 ? x1 : x2;
;           const float im = left + 2.f * (s[nt][0] + s[nt][1] + s[nt][2]) + s[nt][3];
;           LAS float* ip = impx + (wave * 8 + nt) * 64;
;           if (hp == 0) *ip = im; else *ip += im;
;         }
;         f32x4 o[4];
; #pragma unroll
;         for (int dt = 0; dt < 4; ++dt) o[dt] = (f32x4){0.f, 0.f, 0.f, 0.f};
; #pragma unroll
;         for (int st = 0; st < 4; ++st) {
;           if (2 * st * 256 > t0 - 16) continue;
;           const half8 pf = {(h16)s[2 * st][0], (h16)s[2 * st][1], (h16)s[2 * st][2], (h16)s[2 * st][3],
;                             (h16)s[2 * st + 1][0], (h16)s[2 * st + 1][1], (h16)s[2 * st + 1][2], (h16)s[2 * st + 1][3]};
; #pragma unroll
;           for (int dt = 0; dt < 4; ++dt) {
;             const half8 vf = *(const half8*)(vcb + ((st * 64) + dt * 16 + fr) * 32 + fq * 8);
;             o[dt] = MFMA16(vf, pf, o[dt]);
;           }
;         }
.LBB0_324:
	v_mov_b32_e32 v0, v5
	s_waitcnt lgkmcnt(0)
	s_nop 1
	v_permlane16_swap_b32_e32 v0, v5
	v_add_f32_e32 v0, v5, v0
	v_mov_b32_e32 v5, v0
	s_waitcnt lgkmcnt(0)
	s_nop 1
	v_permlane32_swap_b32_e32 v5, v0
	v_add_f32_e32 v0, v0, v5
	v_div_scale_f32 v5, s[0:1], v0, v0, 1.0
	v_rcp_f32_e32 v24, v5
	v_div_scale_f32 v25, vcc, 1.0, v0, 1.0
	v_fma_f32 v26, -v5, v24, 1.0
	v_fmac_f32_e32 v24, v26, v24
	v_mul_f32_e32 v26, v25, v24
	v_fma_f32 v27, -v5, v26, v25
	v_fmac_f32_e32 v26, v27, v24
	v_fma_f32 v5, -v5, v26, v25
	v_div_fmas_f32 v5, v5, v24, v26
	v_div_fixup_f32 v5, v5, v0, 1.0
	v_cmp_lt_f32_e32 vcc, 0, v0
	s_nop 1
	v_cndmask_b32_e32 v0, 0, v5, vcc
	v_cndmask_b32_e64 v5, 0, 1, s[12:13]
	v_pk_mul_f32 v[2:3], v[2:3], v[0:1] op_sel_hi:[1,0]
	v_pk_mul_f32 v[24:25], v[28:29], v[0:1] op_sel_hi:[1,0]
	v_pk_mul_f32 v[26:27], v[30:31], v[0:1] op_sel_hi:[1,0]
	v_pk_mul_f32 v[28:29], v[6:7], v[0:1] op_sel_hi:[1,0]
	v_pk_mul_f32 v[54:55], v[44:45], v[0:1] op_sel_hi:[1,0]
	v_pk_mul_f32 v[56:57], v[38:39], v[0:1] op_sel_hi:[1,0]
	v_pk_mul_f32 v[58:59], v[46:47], v[0:1] op_sel_hi:[1,0]
	v_pk_mul_f32 v[60:61], v[36:37], v[0:1] op_sel_hi:[1,0]
	v_pk_mul_f32 v[46:47], v[50:51], v[0:1] op_sel_hi:[1,0]
	v_pk_mul_f32 v[48:49], v[48:49], v[0:1] op_sel_hi:[1,0]
	v_pk_mul_f32 v[50:51], v[40:41], v[0:1] op_sel_hi:[1,0]
	v_pk_mul_f32 v[52:53], v[52:53], v[0:1] op_sel_hi:[1,0]
	v_pk_mul_f32 v[6:7], v[34:35], v[0:1] op_sel_hi:[1,0]
	v_pk_mul_f32 v[40:41], v[32:33], v[0:1] op_sel_hi:[1,0]
	v_pk_mul_f32 v[42:43], v[42:43], v[0:1] op_sel_hi:[1,0]
	v_cmp_ne_u32_e64 s[0:1], 1, v5
	s_andn2_b64 vcc, exec, s[12:13]
	v_pk_mul_f32 v[44:45], v[62:63], v[0:1] op_sel_hi:[1,0]
	v_mov_b32_e32 v107, v1
	v_lshl_add_u64 v[246:247], v[104:105], 0, v[106:107]
	global_load_dwordx4 v[84:87], v[246:247], off
	global_load_dwordx4 v[88:91], v[246:247], off offset:1024
	global_load_dwordx4 v[92:95], v[246:247], off offset:2048
	global_load_dwordx4 v[96:99], v[246:247], off offset:3072
	s_cbranch_vccnz .LBB0_326
	ds_bpermute_b32 v62, v181, v3
	ds_bpermute_b32 v63, v181, v27
	ds_bpermute_b32 v64, v181, v55
	ds_bpermute_b32 v65, v181, v59
	ds_bpermute_b32 v66, v181, v47
	ds_bpermute_b32 v67, v181, v51
	ds_bpermute_b32 v68, v181, v7
	ds_bpermute_b32 v69, v181, v43
	ds_read2st64_b32 v[32:33], v155 offset0:88 offset1:89
	ds_read2st64_b32 v[34:35], v155 offset0:90 offset1:91
	ds_read2st64_b32 v[36:37], v155 offset0:92 offset1:93
	ds_read2st64_b32 v[38:39], v155 offset0:94 offset1:95
	s_waitcnt lgkmcnt(0)
	v_add_f32_e32 v5, v24, v25
	v_add_f32_e32 v5, v2, v5
	v_add_f32_e32 v31, v28, v29
	v_add_f32_e32 v31, v26, v31
	v_cndmask_b32_e64 v30, v62, 0, s[62:63]
	v_fmac_f32_e32 v30, 2.0, v5
	v_add_f32_e32 v5, v3, v30
	v_add_f32_e32 v5, v32, v5
	v_cndmask_b32_e64 v0, v63, v62, s[62:63]
	v_fmac_f32_e32 v0, 2.0, v31
	v_add_f32_e32 v0, v27, v0
	v_add_f32_e32 v0, v33, v0
	ds_write2st64_b32 v155, v5, v0 offset0:88 offset1:89
	v_add_f32_e32 v5, v56, v57
	v_add_f32_e32 v5, v54, v5
	v_add_f32_e32 v31, v60, v61
	v_add_f32_e32 v31, v58, v31
	v_cndmask_b32_e64 v30, v64, v63, s[62:63]
	v_fmac_f32_e32 v30, 2.0, v5
	v_add_f32_e32 v5, v55, v30
	v_add_f32_e32 v5, v34, v5
	v_cndmask_b32_e64 v0, v65, v64, s[62:63]
	v_fmac_f32_e32 v0, 2.0, v31
	v_add_f32_e32 v0, v59, v0
	v_add_f32_e32 v0, v35, v0
	ds_write2st64_b32 v155, v5, v0 offset0:90 offset1:91
	v_add_f32_e32 v5, v48, v49
	v_add_f32_e32 v5, v46, v5
	v_add_f32_e32 v31, v52, v53
	v_add_f32_e32 v31, v50, v31
	v_cndmask_b32_e64 v30, v66, v65, s[62:63]
	v_fmac_f32_e32 v30, 2.0, v5
	v_add_f32_e32 v5, v47, v30
	v_add_f32_e32 v5, v36, v5
	v_cndmask_b32_e64 v0, v67, v66, s[62:63]
	v_fmac_f32_e32 v0, 2.0, v31
	v_add_f32_e32 v0, v51, v0
	v_add_f32_e32 v0, v37, v0
	ds_write2st64_b32 v155, v5, v0 offset0:92 offset1:93
	v_add_f32_e32 v5, v40, v41
	v_add_f32_e32 v5, v6, v5
	v_add_f32_e32 v31, v44, v45
	v_add_f32_e32 v31, v42, v31
	v_cndmask_b32_e64 v30, v68, v67, s[62:63]
	v_fmac_f32_e32 v30, 2.0, v5
	v_add_f32_e32 v5, v7, v30
	v_add_f32_e32 v5, v38, v5
	v_cndmask_b32_e64 v0, v69, v68, s[62:63]
	v_fmac_f32_e32 v0, 2.0, v31
	v_add_f32_e32 v0, v43, v0
	v_add_f32_e32 v0, v39, v0
	ds_write2st64_b32 v155, v5, v0 offset0:94 offset1:95
.LBB0_326:
	s_and_b64 vcc, exec, s[40:41]
	s_cbranch_vccnz .LBB0_373
	v_cvt_pk_f16_f32 v69, v26, v27
	v_cvt_pk_f16_f32 v68, v28, v29
	v_cvt_pk_f16_f32 v67, v2, v3
	v_cvt_pk_f16_f32 v66, v24, v25
	s_waitcnt vmcnt(0) lgkmcnt(0)
	s_nop 0
	v_mfma_f32_16x16x32_f16 v[36:39], v[84:87], v[66:69], 0
	v_mfma_f32_16x16x32_f16 v[28:31], v[88:91], v[66:69], 0
	v_mfma_f32_16x16x32_f16 v[32:35], v[92:95], v[66:69], 0
	v_mfma_f32_16x16x32_f16 v[24:27], v[96:99], v[66:69], 0
	s_and_b64 vcc, exec, s[42:43]
	s_cbranch_vccnz .LBB0_329
